# SWIGLU epilogue row loops unrolled: all LDS row/rss reads issued up front, rs chains interleaved (arithmetic unchanged)
# speedup vs baseline: 1.1178x; 1.0152x over previous
; DI void epi_slab(const GemmCfg c, const f32x16 (&acc)[4], float* sW, const float* rss, const size_t row0, const int g, const int lane,
;                  float* const g_h, u16* const g_hb, float* const g_out, const int final_out) {
;     ...
;   if (c.epi == EPI_SWIGLU) {
;     const int c4 = (ln_ & 15) * 4;
; #pragma unroll 2
;     for (int it = 0; it < 8; ++it) {
;       const int r = (ln_ >> 4) + 4 * it;
;       const float rs = rsqrtf(rss[r] * invK + 1e-6f);
;       f32x4 a = *(const f32x4*)(sW + r * 132 + c4);
;       f32x4 b = *(const f32x4*)(sW + r * 132 + 64 + c4);
;       float y[4];
; #pragma unroll
;       for (int e = 0; e < 4; ++e) { float av = a[e] * rs, bv = b[e] * rs; y[e] = av * __builtin_amdgcn_rcpf(1.f + __expf(-av)) * bv; }
;       *(u32x2*)(c.o16 + (row0 + r) * DFF + g * 64 + c4) = MK2(pack2(y[0], y[1]), pack2(y[2], y[3]));
;     }
.LBB0_277:
	v_add_u32_e32 v160, 0x24000, v67
	ds_read_b32 v68, v160
	ds_read_b32 v70, v160 offset:16
	ds_read_b32 v72, v160 offset:32
	ds_read_b32 v74, v160 offset:48
	ds_read_b32 v76, v160 offset:64
	ds_read_b32 v78, v160 offset:80
	ds_read_b32 v80, v160 offset:96
	ds_read_b32 v82, v160 offset:112
	ds_read_b128 v[84:87], v66
	ds_read_b128 v[88:91], v66 offset:256
	ds_read_b128 v[92:95], v66 offset:2112
	ds_read_b128 v[96:99], v66 offset:2368
	ds_read_b128 v[100:103], v66 offset:4224
	ds_read_b128 v[104:107], v66 offset:4480
	ds_read_b128 v[108:111], v66 offset:6336
	s_waitcnt lgkmcnt(7)
	s_mov_b32 s8, 0x0
	s_mov_b32 s9, 0
	v_fmaak_f32 v68, v191, v68, 0x358637bd
	v_fmaak_f32 v70, v191, v70, 0x358637bd
	v_cmp_gt_f32_e32 vcc, s33, v68
	v_cmp_gt_f32_e64 s[14:15], s33, v70
	v_mul_f32_e32 v69, 0x4b800000, v68
	v_mul_f32_e32 v71, 0x4b800000, v70
	v_cndmask_b32_e32 v68, v68, v69, vcc
	v_cndmask_b32_e64 v70, v70, v71, s[14:15]
	v_rsq_f32_e32 v68, v68
	v_rsq_f32_e32 v70, v70
	s_nop 0
	v_mul_f32_e32 v69, 0x45800000, v68
	v_mul_f32_e32 v71, 0x45800000, v70
	v_cndmask_b32_e32 v68, v68, v69, vcc
	v_cndmask_b32_e64 v70, v70, v71, s[14:15]
	v_fmaak_f32 v72, v191, v72, 0x358637bd
	v_fmaak_f32 v74, v191, v74, 0x358637bd
	v_cmp_gt_f32_e32 vcc, s33, v72
	v_cmp_gt_f32_e64 s[14:15], s33, v74
	v_mul_f32_e32 v73, 0x4b800000, v72
	v_mul_f32_e32 v75, 0x4b800000, v74
	v_cndmask_b32_e32 v72, v72, v73, vcc
	v_cndmask_b32_e64 v74, v74, v75, s[14:15]
	v_rsq_f32_e32 v72, v72
	v_rsq_f32_e32 v74, v74
	s_nop 0
	v_mul_f32_e32 v73, 0x45800000, v72
	v_mul_f32_e32 v75, 0x45800000, v74
	v_cndmask_b32_e32 v72, v72, v73, vcc
	v_cndmask_b32_e64 v74, v74, v75, s[14:15]
	v_fmaak_f32 v76, v191, v76, 0x358637bd
	v_fmaak_f32 v78, v191, v78, 0x358637bd
	v_cmp_gt_f32_e32 vcc, s33, v76
	v_cmp_gt_f32_e64 s[14:15], s33, v78
	v_mul_f32_e32 v77, 0x4b800000, v76
	v_mul_f32_e32 v79, 0x4b800000, v78
	v_cndmask_b32_e32 v76, v76, v77, vcc
	v_cndmask_b32_e64 v78, v78, v79, s[14:15]
	v_rsq_f32_e32 v76, v76
	v_rsq_f32_e32 v78, v78
	s_nop 0
	v_mul_f32_e32 v77, 0x45800000, v76
	v_mul_f32_e32 v79, 0x45800000, v78
	v_cndmask_b32_e32 v76, v76, v77, vcc
	v_cndmask_b32_e64 v78, v78, v79, s[14:15]
	v_fmaak_f32 v80, v191, v80, 0x358637bd
	v_fmaak_f32 v82, v191, v82, 0x358637bd
	v_cmp_gt_f32_e32 vcc, s33, v80
	v_cmp_gt_f32_e64 s[14:15], s33, v82
	v_mul_f32_e32 v81, 0x4b800000, v80
	v_mul_f32_e32 v83, 0x4b800000, v82
	v_cndmask_b32_e32 v80, v80, v81, vcc
	v_cndmask_b32_e64 v82, v82, v83, s[14:15]
	v_rsq_f32_e32 v80, v80
	v_rsq_f32_e32 v82, v82
	s_nop 0
	v_mul_f32_e32 v81, 0x45800000, v80
	v_mul_f32_e32 v83, 0x45800000, v82
	v_cndmask_b32_e32 v80, v80, v81, vcc
	v_cndmask_b32_e64 v82, v82, v83, s[14:15]
	s_waitcnt lgkmcnt(6)
	ds_read_b128 v[112:115], v66 offset:6592
	ds_read_b128 v[116:119], v66 offset:8448
	ds_read_b128 v[120:123], v66 offset:8704
	ds_read_b128 v[124:127], v66 offset:10560
	ds_read_b128 v[136:139], v66 offset:10816
	ds_read_b128 v[140:143], v66 offset:12672
	ds_read_b128 v[144:147], v66 offset:12928
	ds_read_b128 v[148:151], v66 offset:14784
	ds_read_b128 v[152:155], v66 offset:15040
	s_waitcnt lgkmcnt(14)
	v_pk_mul_f32 v[84:85], v[84:85], v[68:69] op_sel_hi:[1,0]
	v_pk_mul_f32 v[86:87], v[86:87], v[68:69] op_sel_hi:[1,0]
	v_pk_mul_f32 v[88:89], v[88:89], v[68:69] op_sel_hi:[1,0]
	v_pk_mul_f32 v[90:91], v[90:91], v[68:69] op_sel_hi:[1,0]
	v_mul_f32_e32 v156, 0xbfb8aa3b, v84
	v_mul_f32_e32 v157, 0xbfb8aa3b, v85
	v_mul_f32_e32 v158, 0xbfb8aa3b, v86
	v_mul_f32_e32 v159, 0xbfb8aa3b, v87
	v_exp_f32_e32 v156, v156
	v_exp_f32_e32 v157, v157
	v_exp_f32_e32 v158, v158
	v_exp_f32_e32 v159, v159
	v_add_f32_e32 v156, 1.0, v156
	v_add_f32_e32 v157, 1.0, v157
	v_add_f32_e32 v158, 1.0, v158
	v_add_f32_e32 v159, 1.0, v159
	v_rcp_f32_e32 v156, v156
	v_rcp_f32_e32 v157, v157
	v_rcp_f32_e32 v158, v158
	v_rcp_f32_e32 v159, v159
	v_lshl_add_u64 v[160:161], v[64:65], 0, s[8:9]
	v_pk_mul_f32 v[84:85], v[84:85], v[156:157]
	v_pk_mul_f32 v[86:87], v[86:87], v[158:159]
	v_pk_mul_f32 v[84:85], v[88:89], v[84:85]
	v_pk_mul_f32 v[86:87], v[90:91], v[86:87]
	s_add_u32 s8, s8, 0x5800
	s_addc_u32 s9, s9, 0
	v_cvt_pk_bf16_f32 v84, v84, v85
	v_cvt_pk_bf16_f32 v85, v86, v87
	global_store_dwordx2 v[160:161], v[84:85], off
	s_waitcnt lgkmcnt(12)
	v_pk_mul_f32 v[92:93], v[92:93], v[70:71] op_sel_hi:[1,0]
	v_pk_mul_f32 v[94:95], v[94:95], v[70:71] op_sel_hi:[1,0]
	v_pk_mul_f32 v[96:97], v[96:97], v[70:71] op_sel_hi:[1,0]
	v_pk_mul_f32 v[98:99], v[98:99], v[70:71] op_sel_hi:[1,0]
	v_mul_f32_e32 v156, 0xbfb8aa3b, v92
	v_mul_f32_e32 v157, 0xbfb8aa3b, v93
	v_mul_f32_e32 v158, 0xbfb8aa3b, v94
	v_mul_f32_e32 v159, 0xbfb8aa3b, v95
	v_exp_f32_e32 v156, v156
	v_exp_f32_e32 v157, v157
	v_exp_f32_e32 v158, v158
	v_exp_f32_e32 v159, v159
	v_add_f32_e32 v156, 1.0, v156
	v_add_f32_e32 v157, 1.0, v157
	v_add_f32_e32 v158, 1.0, v158
	v_add_f32_e32 v159, 1.0, v159
	v_rcp_f32_e32 v156, v156
	v_rcp_f32_e32 v157, v157
	v_rcp_f32_e32 v158, v158
	v_rcp_f32_e32 v159, v159
	v_lshl_add_u64 v[160:161], v[64:65], 0, s[8:9]
	v_pk_mul_f32 v[92:93], v[92:93], v[156:157]
	v_pk_mul_f32 v[94:95], v[94:95], v[158:159]
	v_pk_mul_f32 v[92:93], v[96:97], v[92:93]
	v_pk_mul_f32 v[94:95], v[98:99], v[94:95]
	s_add_u32 s8, s8, 0x5800
	s_addc_u32 s9, s9, 0
	v_cvt_pk_bf16_f32 v92, v92, v93
	v_cvt_pk_bf16_f32 v93, v94, v95
	global_store_dwordx2 v[160:161], v[92:93], off
	s_waitcnt lgkmcnt(10)
; DI void epi_slab(const GemmCfg c, const f32x16 (&acc)[4], float* sW, const float* rss, const size_t row0, const int g, const int lane,
;                  float* const g_h, u16* const g_hb, float* const g_out, const int final_out) {
;     ...
;   if (c.epi == EPI_SWIGLU) {
;     const int c4 = (ln_ & 15) * 4;
; #pragma unroll 2
;     for (int it = 0; it < 8; ++it) {
;       const int r = (ln_ >> 4) + 4 * it;
;       const float rs = rsqrtf(rss[r] * invK + 1e-6f);
;       f32x4 a = *(const f32x4*)(sW + r * 132 + c4);
;       f32x4 b = *(const f32x4*)(sW + r * 132 + 64 + c4);
;       float y[4];
; #pragma unroll
;       for (int e = 0; e < 4; ++e) { float av = a[e] * rs, bv = b[e] * rs; y[e] = av * __builtin_amdgcn_rcpf(1.f + __expf(-av)) * bv; }
;       *(u32x2*)(c.o16 + (row0 + r) * DFF + g * 64 + c4) = MK2(pack2(y[0], y[1]), pack2(y[2], y[3]));
;     }
	v_pk_mul_f32 v[100:101], v[100:101], v[72:73] op_sel_hi:[1,0]
	v_pk_mul_f32 v[102:103], v[102:103], v[72:73] op_sel_hi:[1,0]
	v_pk_mul_f32 v[104:105], v[104:105], v[72:73] op_sel_hi:[1,0]
	v_pk_mul_f32 v[106:107], v[106:107], v[72:73] op_sel_hi:[1,0]
	v_mul_f32_e32 v156, 0xbfb8aa3b, v100
	v_mul_f32_e32 v157, 0xbfb8aa3b, v101
	v_mul_f32_e32 v158, 0xbfb8aa3b, v102
	v_mul_f32_e32 v159, 0xbfb8aa3b, v103
	v_exp_f32_e32 v156, v156
	v_exp_f32_e32 v157, v157
	v_exp_f32_e32 v158, v158
	v_exp_f32_e32 v159, v159
	v_add_f32_e32 v156, 1.0, v156
	v_add_f32_e32 v157, 1.0, v157
	v_add_f32_e32 v158, 1.0, v158
	v_add_f32_e32 v159, 1.0, v159
	v_rcp_f32_e32 v156, v156
	v_rcp_f32_e32 v157, v157
	v_rcp_f32_e32 v158, v158
	v_rcp_f32_e32 v159, v159
	v_lshl_add_u64 v[160:161], v[64:65], 0, s[8:9]
	v_pk_mul_f32 v[100:101], v[100:101], v[156:157]
	v_pk_mul_f32 v[102:103], v[102:103], v[158:159]
	v_pk_mul_f32 v[100:101], v[104:105], v[100:101]
	v_pk_mul_f32 v[102:103], v[106:107], v[102:103]
	s_add_u32 s8, s8, 0x5800
	s_addc_u32 s9, s9, 0
	v_cvt_pk_bf16_f32 v100, v100, v101
	v_cvt_pk_bf16_f32 v101, v102, v103
	global_store_dwordx2 v[160:161], v[100:101], off
	s_waitcnt lgkmcnt(8)
	v_pk_mul_f32 v[108:109], v[108:109], v[74:75] op_sel_hi:[1,0]
	v_pk_mul_f32 v[110:111], v[110:111], v[74:75] op_sel_hi:[1,0]
	v_pk_mul_f32 v[112:113], v[112:113], v[74:75] op_sel_hi:[1,0]
	v_pk_mul_f32 v[114:115], v[114:115], v[74:75] op_sel_hi:[1,0]
	v_mul_f32_e32 v156, 0xbfb8aa3b, v108
	v_mul_f32_e32 v157, 0xbfb8aa3b, v109
	v_mul_f32_e32 v158, 0xbfb8aa3b, v110
	v_mul_f32_e32 v159, 0xbfb8aa3b, v111
	v_exp_f32_e32 v156, v156
	v_exp_f32_e32 v157, v157
	v_exp_f32_e32 v158, v158
	v_exp_f32_e32 v159, v159
	v_add_f32_e32 v156, 1.0, v156
	v_add_f32_e32 v157, 1.0, v157
	v_add_f32_e32 v158, 1.0, v158
	v_add_f32_e32 v159, 1.0, v159
	v_rcp_f32_e32 v156, v156
	v_rcp_f32_e32 v157, v157
	v_rcp_f32_e32 v158, v158
	v_rcp_f32_e32 v159, v159
	v_lshl_add_u64 v[160:161], v[64:65], 0, s[8:9]
	v_pk_mul_f32 v[108:109], v[108:109], v[156:157]
	v_pk_mul_f32 v[110:111], v[110:111], v[158:159]
	v_pk_mul_f32 v[108:109], v[112:113], v[108:109]
	v_pk_mul_f32 v[110:111], v[114:115], v[110:111]
	s_add_u32 s8, s8, 0x5800
	s_addc_u32 s9, s9, 0
	v_cvt_pk_bf16_f32 v108, v108, v109
	v_cvt_pk_bf16_f32 v109, v110, v111
	global_store_dwordx2 v[160:161], v[108:109], off
	s_waitcnt lgkmcnt(6)
	v_pk_mul_f32 v[116:117], v[116:117], v[76:77] op_sel_hi:[1,0]
	v_pk_mul_f32 v[118:119], v[118:119], v[76:77] op_sel_hi:[1,0]
	v_pk_mul_f32 v[120:121], v[120:121], v[76:77] op_sel_hi:[1,0]
	v_pk_mul_f32 v[122:123], v[122:123], v[76:77] op_sel_hi:[1,0]
	v_mul_f32_e32 v156, 0xbfb8aa3b, v116
	v_mul_f32_e32 v157, 0xbfb8aa3b, v117
	v_mul_f32_e32 v158, 0xbfb8aa3b, v118
	v_mul_f32_e32 v159, 0xbfb8aa3b, v119
	v_exp_f32_e32 v156, v156
	v_exp_f32_e32 v157, v157
	v_exp_f32_e32 v158, v158
	v_exp_f32_e32 v159, v159
	v_add_f32_e32 v156, 1.0, v156
	v_add_f32_e32 v157, 1.0, v157
	v_add_f32_e32 v158, 1.0, v158
	v_add_f32_e32 v159, 1.0, v159
	v_rcp_f32_e32 v156, v156
	v_rcp_f32_e32 v157, v157
	v_rcp_f32_e32 v158, v158
	v_rcp_f32_e32 v159, v159
	v_lshl_add_u64 v[160:161], v[64:65], 0, s[8:9]
	v_pk_mul_f32 v[116:117], v[116:117], v[156:157]
	v_pk_mul_f32 v[118:119], v[118:119], v[158:159]
	v_pk_mul_f32 v[116:117], v[120:121], v[116:117]
	v_pk_mul_f32 v[118:119], v[122:123], v[118:119]
	s_add_u32 s8, s8, 0x5800
	s_addc_u32 s9, s9, 0
	v_cvt_pk_bf16_f32 v116, v116, v117
	v_cvt_pk_bf16_f32 v117, v118, v119
	global_store_dwordx2 v[160:161], v[116:117], off
	s_waitcnt lgkmcnt(4)
	v_pk_mul_f32 v[124:125], v[124:125], v[78:79] op_sel_hi:[1,0]
	v_pk_mul_f32 v[126:127], v[126:127], v[78:79] op_sel_hi:[1,0]
	v_pk_mul_f32 v[136:137], v[136:137], v[78:79] op_sel_hi:[1,0]
	v_pk_mul_f32 v[138:139], v[138:139], v[78:79] op_sel_hi:[1,0]
	v_mul_f32_e32 v156, 0xbfb8aa3b, v124
	v_mul_f32_e32 v157, 0xbfb8aa3b, v125
	v_mul_f32_e32 v158, 0xbfb8aa3b, v126
	v_mul_f32_e32 v159, 0xbfb8aa3b, v127
	v_exp_f32_e32 v156, v156
	v_exp_f32_e32 v157, v157
	v_exp_f32_e32 v158, v158
	v_exp_f32_e32 v159, v159
	v_add_f32_e32 v156, 1.0, v156
	v_add_f32_e32 v157, 1.0, v157
	v_add_f32_e32 v158, 1.0, v158
	v_add_f32_e32 v159, 1.0, v159
	v_rcp_f32_e32 v156, v156
	v_rcp_f32_e32 v157, v157
	v_rcp_f32_e32 v158, v158
	v_rcp_f32_e32 v159, v159
	v_lshl_add_u64 v[160:161], v[64:65], 0, s[8:9]
	v_pk_mul_f32 v[124:125], v[124:125], v[156:157]
	v_pk_mul_f32 v[126:127], v[126:127], v[158:159]
	v_pk_mul_f32 v[124:125], v[136:137], v[124:125]
	v_pk_mul_f32 v[126:127], v[138:139], v[126:127]
	s_add_u32 s8, s8, 0x5800
	s_addc_u32 s9, s9, 0
	v_cvt_pk_bf16_f32 v124, v124, v125
	v_cvt_pk_bf16_f32 v125, v126, v127
	global_store_dwordx2 v[160:161], v[124:125], off
	s_waitcnt lgkmcnt(2)
	v_pk_mul_f32 v[140:141], v[140:141], v[80:81] op_sel_hi:[1,0]
	v_pk_mul_f32 v[142:143], v[142:143], v[80:81] op_sel_hi:[1,0]
	v_pk_mul_f32 v[144:145], v[144:145], v[80:81] op_sel_hi:[1,0]
	v_pk_mul_f32 v[146:147], v[146:147], v[80:81] op_sel_hi:[1,0]
	v_mul_f32_e32 v156, 0xbfb8aa3b, v140
	v_mul_f32_e32 v157, 0xbfb8aa3b, v141
	v_mul_f32_e32 v158, 0xbfb8aa3b, v142
	v_mul_f32_e32 v159, 0xbfb8aa3b, v143
	v_exp_f32_e32 v156, v156
	v_exp_f32_e32 v157, v157
	v_exp_f32_e32 v158, v158
	v_exp_f32_e32 v159, v159
	v_add_f32_e32 v156, 1.0, v156
	v_add_f32_e32 v157, 1.0, v157
	v_add_f32_e32 v158, 1.0, v158
	v_add_f32_e32 v159, 1.0, v159
	v_rcp_f32_e32 v156, v156
	v_rcp_f32_e32 v157, v157
	v_rcp_f32_e32 v158, v158
	v_rcp_f32_e32 v159, v159
	v_lshl_add_u64 v[160:161], v[64:65], 0, s[8:9]
	v_pk_mul_f32 v[140:141], v[140:141], v[156:157]
	v_pk_mul_f32 v[142:143], v[142:143], v[158:159]
	v_pk_mul_f32 v[140:141], v[144:145], v[140:141]
	v_pk_mul_f32 v[142:143], v[146:147], v[142:143]
	s_add_u32 s8, s8, 0x5800
	s_addc_u32 s9, s9, 0
	v_cvt_pk_bf16_f32 v140, v140, v141
	v_cvt_pk_bf16_f32 v141, v142, v143
	global_store_dwordx2 v[160:161], v[140:141], off
	s_waitcnt lgkmcnt(0)
	v_pk_mul_f32 v[148:149], v[148:149], v[82:83] op_sel_hi:[1,0]
	v_pk_mul_f32 v[150:151], v[150:151], v[82:83] op_sel_hi:[1,0]
	v_pk_mul_f32 v[152:153], v[152:153], v[82:83] op_sel_hi:[1,0]
	v_pk_mul_f32 v[154:155], v[154:155], v[82:83] op_sel_hi:[1,0]
	v_mul_f32_e32 v156, 0xbfb8aa3b, v148
	v_mul_f32_e32 v157, 0xbfb8aa3b, v149
	v_mul_f32_e32 v158, 0xbfb8aa3b, v150
	v_mul_f32_e32 v159, 0xbfb8aa3b, v151
	v_exp_f32_e32 v156, v156
	v_exp_f32_e32 v157, v157
	v_exp_f32_e32 v158, v158
	v_exp_f32_e32 v159, v159
	v_add_f32_e32 v156, 1.0, v156
	v_add_f32_e32 v157, 1.0, v157
	v_add_f32_e32 v158, 1.0, v158
	v_add_f32_e32 v159, 1.0, v159
	v_rcp_f32_e32 v156, v156
	v_rcp_f32_e32 v157, v157
	v_rcp_f32_e32 v158, v158
	v_rcp_f32_e32 v159, v159
	v_lshl_add_u64 v[160:161], v[64:65], 0, s[8:9]
	v_pk_mul_f32 v[148:149], v[148:149], v[156:157]
	v_pk_mul_f32 v[150:151], v[150:151], v[158:159]
	v_pk_mul_f32 v[148:149], v[152:153], v[148:149]
	v_pk_mul_f32 v[150:151], v[154:155], v[150:151]
	s_add_u32 s8, s8, 0x5800
	s_addc_u32 s9, s9, 0
	v_cvt_pk_bf16_f32 v148, v148, v149
	v_cvt_pk_bf16_f32 v149, v150, v151
	global_store_dwordx2 v[160:161], v[148:149], off

; DI void epi_slab(const GemmCfg c, const f32x16 (&acc)[4], float* sW, const float* rss, const size_t row0, const int g, const int lane,
;                  float* const g_h, u16* const g_hb, float* const g_out, const int final_out) {
;     ...
;   if (c.epi == EPI_SWIGLU) {
;     const int c4 = (ln_ & 15) * 4;
; #pragma unroll 2
;     for (int it = 0; it < 8; ++it) {
;       const int r = (ln_ >> 4) + 4 * it;
;       const float rs = rsqrtf(rss[r] * invK + 1e-6f);
;       f32x4 a = *(const f32x4*)(sW + r * 132 + c4);
;       f32x4 b = *(const f32x4*)(sW + r * 132 + 64 + c4);
;       float y[4];
; #pragma unroll
;       for (int e = 0; e < 4; ++e) { float av = a[e] * rs, bv = b[e] * rs; y[e] = av * __builtin_amdgcn_rcpf(1.f + __expf(-av)) * bv; }
;       *(u32x2*)(c.o16 + (row0 + r) * DFF + g * 64 + c4) = MK2(pack2(y[0], y[1]), pack2(y[2], y[3]));
;     }
.LBB0_432:
	v_add_u32_e32 v160, 0x24080, v3
	ds_read_b32 v4, v160
	ds_read_b32 v6, v160 offset:16
	ds_read_b32 v8, v160 offset:32
	ds_read_b32 v10, v160 offset:48
	ds_read_b32 v12, v160 offset:64
	ds_read_b32 v14, v160 offset:80
	ds_read_b32 v16, v160 offset:96
	ds_read_b32 v18, v160 offset:112
	ds_read_b128 v[20:23], v2
	ds_read_b128 v[24:27], v2 offset:256
	ds_read_b128 v[28:31], v2 offset:2112
	ds_read_b128 v[32:35], v2 offset:2368
	ds_read_b128 v[36:39], v2 offset:4224
	ds_read_b128 v[40:43], v2 offset:4480
	ds_read_b128 v[44:47], v2 offset:6336
	s_waitcnt lgkmcnt(7)
	s_mov_b32 s4, 0x2c000
	s_mov_b32 s5, 0
	v_fmaak_f32 v4, v191, v4, 0x358637bd
	v_fmaak_f32 v6, v191, v6, 0x358637bd
	v_cmp_gt_f32_e32 vcc, s33, v4
	v_cmp_gt_f32_e64 s[0:1], s33, v6
	v_mul_f32_e32 v5, 0x4b800000, v4
	v_mul_f32_e32 v7, 0x4b800000, v6
	v_cndmask_b32_e32 v4, v4, v5, vcc
	v_cndmask_b32_e64 v6, v6, v7, s[0:1]
	v_rsq_f32_e32 v4, v4
	v_rsq_f32_e32 v6, v6
	s_nop 0
	v_mul_f32_e32 v5, 0x45800000, v4
	v_mul_f32_e32 v7, 0x45800000, v6
	v_cndmask_b32_e32 v4, v4, v5, vcc
	v_cndmask_b32_e64 v6, v6, v7, s[0:1]
	v_fmaak_f32 v8, v191, v8, 0x358637bd
	v_fmaak_f32 v10, v191, v10, 0x358637bd
	v_cmp_gt_f32_e32 vcc, s33, v8
	v_cmp_gt_f32_e64 s[0:1], s33, v10
	v_mul_f32_e32 v9, 0x4b800000, v8
	v_mul_f32_e32 v11, 0x4b800000, v10
	v_cndmask_b32_e32 v8, v8, v9, vcc
	v_cndmask_b32_e64 v10, v10, v11, s[0:1]
	v_rsq_f32_e32 v8, v8
	v_rsq_f32_e32 v10, v10
	s_nop 0
	v_mul_f32_e32 v9, 0x45800000, v8
	v_mul_f32_e32 v11, 0x45800000, v10
	v_cndmask_b32_e32 v8, v8, v9, vcc
	v_cndmask_b32_e64 v10, v10, v11, s[0:1]
	v_fmaak_f32 v12, v191, v12, 0x358637bd
	v_fmaak_f32 v14, v191, v14, 0x358637bd
	v_cmp_gt_f32_e32 vcc, s33, v12
	v_cmp_gt_f32_e64 s[0:1], s33, v14
	v_mul_f32_e32 v13, 0x4b800000, v12
	v_mul_f32_e32 v15, 0x4b800000, v14
	v_cndmask_b32_e32 v12, v12, v13, vcc
	v_cndmask_b32_e64 v14, v14, v15, s[0:1]
	v_rsq_f32_e32 v12, v12
	v_rsq_f32_e32 v14, v14
	s_nop 0
	v_mul_f32_e32 v13, 0x45800000, v12
	v_mul_f32_e32 v15, 0x45800000, v14
	v_cndmask_b32_e32 v12, v12, v13, vcc
	v_cndmask_b32_e64 v14, v14, v15, s[0:1]
	v_fmaak_f32 v16, v191, v16, 0x358637bd
	v_fmaak_f32 v18, v191, v18, 0x358637bd
	v_cmp_gt_f32_e32 vcc, s33, v16
	v_cmp_gt_f32_e64 s[0:1], s33, v18
	v_mul_f32_e32 v17, 0x4b800000, v16
	v_mul_f32_e32 v19, 0x4b800000, v18
	v_cndmask_b32_e32 v16, v16, v17, vcc
	v_cndmask_b32_e64 v18, v18, v19, s[0:1]
	v_rsq_f32_e32 v16, v16
	v_rsq_f32_e32 v18, v18
	s_nop 0
	v_mul_f32_e32 v17, 0x45800000, v16
	v_mul_f32_e32 v19, 0x45800000, v18
	v_cndmask_b32_e32 v16, v16, v17, vcc
	v_cndmask_b32_e64 v18, v18, v19, s[0:1]
	s_waitcnt lgkmcnt(6)
	ds_read_b128 v[48:51], v2 offset:6592
	ds_read_b128 v[52:55], v2 offset:8448
	ds_read_b128 v[56:59], v2 offset:8704
	ds_read_b128 v[60:63], v2 offset:10560
	ds_read_b128 v[136:139], v2 offset:10816
	ds_read_b128 v[140:143], v2 offset:12672
	ds_read_b128 v[144:147], v2 offset:12928
	ds_read_b128 v[148:151], v2 offset:14784
	ds_read_b128 v[152:155], v2 offset:15040
	s_waitcnt lgkmcnt(14)
	v_pk_mul_f32 v[20:21], v[20:21], v[4:5] op_sel_hi:[1,0]
	v_pk_mul_f32 v[22:23], v[22:23], v[4:5] op_sel_hi:[1,0]
	v_pk_mul_f32 v[24:25], v[24:25], v[4:5] op_sel_hi:[1,0]
	v_pk_mul_f32 v[26:27], v[26:27], v[4:5] op_sel_hi:[1,0]
	v_mul_f32_e32 v156, 0xbfb8aa3b, v20
	v_mul_f32_e32 v157, 0xbfb8aa3b, v21
	v_mul_f32_e32 v158, 0xbfb8aa3b, v22
	v_mul_f32_e32 v159, 0xbfb8aa3b, v23
	v_exp_f32_e32 v156, v156
	v_exp_f32_e32 v157, v157
	v_exp_f32_e32 v158, v158
	v_exp_f32_e32 v159, v159
	v_add_f32_e32 v156, 1.0, v156
	v_add_f32_e32 v157, 1.0, v157
	v_add_f32_e32 v158, 1.0, v158
	v_add_f32_e32 v159, 1.0, v159
	v_rcp_f32_e32 v156, v156
	v_rcp_f32_e32 v157, v157
	v_rcp_f32_e32 v158, v158
	v_rcp_f32_e32 v159, v159
	v_lshl_add_u64 v[160:161], v[0:1], 0, s[4:5]
	v_pk_mul_f32 v[20:21], v[20:21], v[156:157]
	v_pk_mul_f32 v[22:23], v[22:23], v[158:159]
	v_pk_mul_f32 v[20:21], v[24:25], v[20:21]
	v_pk_mul_f32 v[22:23], v[26:27], v[22:23]
	s_add_u32 s4, s4, 0x5800
	s_addc_u32 s5, s5, 0
	v_cvt_pk_bf16_f32 v20, v20, v21
	v_cvt_pk_bf16_f32 v21, v22, v23
	global_store_dwordx2 v[160:161], v[20:21], off
	s_waitcnt lgkmcnt(12)
	v_pk_mul_f32 v[28:29], v[28:29], v[6:7] op_sel_hi:[1,0]
	v_pk_mul_f32 v[30:31], v[30:31], v[6:7] op_sel_hi:[1,0]
	v_pk_mul_f32 v[32:33], v[32:33], v[6:7] op_sel_hi:[1,0]
	v_pk_mul_f32 v[34:35], v[34:35], v[6:7] op_sel_hi:[1,0]
	v_mul_f32_e32 v156, 0xbfb8aa3b, v28
	v_mul_f32_e32 v157, 0xbfb8aa3b, v29
	v_mul_f32_e32 v158, 0xbfb8aa3b, v30
	v_mul_f32_e32 v159, 0xbfb8aa3b, v31
	v_exp_f32_e32 v156, v156
	v_exp_f32_e32 v157, v157
	v_exp_f32_e32 v158, v158
	v_exp_f32_e32 v159, v159
	v_add_f32_e32 v156, 1.0, v156
	v_add_f32_e32 v157, 1.0, v157
	v_add_f32_e32 v158, 1.0, v158
	v_add_f32_e32 v159, 1.0, v159
	v_rcp_f32_e32 v156, v156
	v_rcp_f32_e32 v157, v157
	v_rcp_f32_e32 v158, v158
	v_rcp_f32_e32 v159, v159
	v_lshl_add_u64 v[160:161], v[0:1], 0, s[4:5]
	v_pk_mul_f32 v[28:29], v[28:29], v[156:157]
	v_pk_mul_f32 v[30:31], v[30:31], v[158:159]
	v_pk_mul_f32 v[28:29], v[32:33], v[28:29]
	v_pk_mul_f32 v[30:31], v[34:35], v[30:31]
	s_add_u32 s4, s4, 0x5800
	s_addc_u32 s5, s5, 0
	v_cvt_pk_bf16_f32 v28, v28, v29
	v_cvt_pk_bf16_f32 v29, v30, v31
	global_store_dwordx2 v[160:161], v[28:29], off
	s_waitcnt lgkmcnt(10)
; DI void epi_slab(const GemmCfg c, const f32x16 (&acc)[4], float* sW, const float* rss, const size_t row0, const int g, const int lane,
;                  float* const g_h, u16* const g_hb, float* const g_out, const int final_out) {
;     ...
;   if (c.epi == EPI_SWIGLU) {
;     const int c4 = (ln_ & 15) * 4;
; #pragma unroll 2
;     for (int it = 0; it < 8; ++it) {
;       const int r = (ln_ >> 4) + 4 * it;
;       const float rs = rsqrtf(rss[r] * invK + 1e-6f);
;       f32x4 a = *(const f32x4*)(sW + r * 132 + c4);
;       f32x4 b = *(const f32x4*)(sW + r * 132 + 64 + c4);
;       float y[4];
; #pragma unroll
;       for (int e = 0; e < 4; ++e) { float av = a[e] * rs, bv = b[e] * rs; y[e] = av * __builtin_amdgcn_rcpf(1.f + __expf(-av)) * bv; }
;       *(u32x2*)(c.o16 + (row0 + r) * DFF + g * 64 + c4) = MK2(pack2(y[0], y[1]), pack2(y[2], y[3]));
;     }
	v_pk_mul_f32 v[36:37], v[36:37], v[8:9] op_sel_hi:[1,0]
	v_pk_mul_f32 v[38:39], v[38:39], v[8:9] op_sel_hi:[1,0]
	v_pk_mul_f32 v[40:41], v[40:41], v[8:9] op_sel_hi:[1,0]
	v_pk_mul_f32 v[42:43], v[42:43], v[8:9] op_sel_hi:[1,0]
	v_mul_f32_e32 v156, 0xbfb8aa3b, v36
	v_mul_f32_e32 v157, 0xbfb8aa3b, v37
	v_mul_f32_e32 v158, 0xbfb8aa3b, v38
	v_mul_f32_e32 v159, 0xbfb8aa3b, v39
	v_exp_f32_e32 v156, v156
	v_exp_f32_e32 v157, v157
	v_exp_f32_e32 v158, v158
	v_exp_f32_e32 v159, v159
	v_add_f32_e32 v156, 1.0, v156
	v_add_f32_e32 v157, 1.0, v157
	v_add_f32_e32 v158, 1.0, v158
	v_add_f32_e32 v159, 1.0, v159
	v_rcp_f32_e32 v156, v156
	v_rcp_f32_e32 v157, v157
	v_rcp_f32_e32 v158, v158
	v_rcp_f32_e32 v159, v159
	v_lshl_add_u64 v[160:161], v[0:1], 0, s[4:5]
	v_pk_mul_f32 v[36:37], v[36:37], v[156:157]
	v_pk_mul_f32 v[38:39], v[38:39], v[158:159]
	v_pk_mul_f32 v[36:37], v[40:41], v[36:37]
	v_pk_mul_f32 v[38:39], v[42:43], v[38:39]
	s_add_u32 s4, s4, 0x5800
	s_addc_u32 s5, s5, 0
	v_cvt_pk_bf16_f32 v36, v36, v37
	v_cvt_pk_bf16_f32 v37, v38, v39
	global_store_dwordx2 v[160:161], v[36:37], off
	s_waitcnt lgkmcnt(8)
	v_pk_mul_f32 v[44:45], v[44:45], v[10:11] op_sel_hi:[1,0]
	v_pk_mul_f32 v[46:47], v[46:47], v[10:11] op_sel_hi:[1,0]
	v_pk_mul_f32 v[48:49], v[48:49], v[10:11] op_sel_hi:[1,0]
	v_pk_mul_f32 v[50:51], v[50:51], v[10:11] op_sel_hi:[1,0]
	v_mul_f32_e32 v156, 0xbfb8aa3b, v44
	v_mul_f32_e32 v157, 0xbfb8aa3b, v45
	v_mul_f32_e32 v158, 0xbfb8aa3b, v46
	v_mul_f32_e32 v159, 0xbfb8aa3b, v47
	v_exp_f32_e32 v156, v156
	v_exp_f32_e32 v157, v157
	v_exp_f32_e32 v158, v158
	v_exp_f32_e32 v159, v159
	v_add_f32_e32 v156, 1.0, v156
	v_add_f32_e32 v157, 1.0, v157
	v_add_f32_e32 v158, 1.0, v158
	v_add_f32_e32 v159, 1.0, v159
	v_rcp_f32_e32 v156, v156
	v_rcp_f32_e32 v157, v157
	v_rcp_f32_e32 v158, v158
	v_rcp_f32_e32 v159, v159
	v_lshl_add_u64 v[160:161], v[0:1], 0, s[4:5]
	v_pk_mul_f32 v[44:45], v[44:45], v[156:157]
	v_pk_mul_f32 v[46:47], v[46:47], v[158:159]
	v_pk_mul_f32 v[44:45], v[48:49], v[44:45]
	v_pk_mul_f32 v[46:47], v[50:51], v[46:47]
	s_add_u32 s4, s4, 0x5800
	s_addc_u32 s5, s5, 0
	v_cvt_pk_bf16_f32 v44, v44, v45
	v_cvt_pk_bf16_f32 v45, v46, v47
	global_store_dwordx2 v[160:161], v[44:45], off
	s_waitcnt lgkmcnt(6)
	v_pk_mul_f32 v[52:53], v[52:53], v[12:13] op_sel_hi:[1,0]
	v_pk_mul_f32 v[54:55], v[54:55], v[12:13] op_sel_hi:[1,0]
	v_pk_mul_f32 v[56:57], v[56:57], v[12:13] op_sel_hi:[1,0]
	v_pk_mul_f32 v[58:59], v[58:59], v[12:13] op_sel_hi:[1,0]
	v_mul_f32_e32 v156, 0xbfb8aa3b, v52
	v_mul_f32_e32 v157, 0xbfb8aa3b, v53
	v_mul_f32_e32 v158, 0xbfb8aa3b, v54
	v_mul_f32_e32 v159, 0xbfb8aa3b, v55
	v_exp_f32_e32 v156, v156
	v_exp_f32_e32 v157, v157
	v_exp_f32_e32 v158, v158
	v_exp_f32_e32 v159, v159
	v_add_f32_e32 v156, 1.0, v156
	v_add_f32_e32 v157, 1.0, v157
	v_add_f32_e32 v158, 1.0, v158
	v_add_f32_e32 v159, 1.0, v159
	v_rcp_f32_e32 v156, v156
	v_rcp_f32_e32 v157, v157
	v_rcp_f32_e32 v158, v158
	v_rcp_f32_e32 v159, v159
	v_lshl_add_u64 v[160:161], v[0:1], 0, s[4:5]
	v_pk_mul_f32 v[52:53], v[52:53], v[156:157]
	v_pk_mul_f32 v[54:55], v[54:55], v[158:159]
	v_pk_mul_f32 v[52:53], v[56:57], v[52:53]
	v_pk_mul_f32 v[54:55], v[58:59], v[54:55]
	s_add_u32 s4, s4, 0x5800
	s_addc_u32 s5, s5, 0
	v_cvt_pk_bf16_f32 v52, v52, v53
	v_cvt_pk_bf16_f32 v53, v54, v55
	global_store_dwordx2 v[160:161], v[52:53], off
	s_waitcnt lgkmcnt(4)
	v_pk_mul_f32 v[60:61], v[60:61], v[14:15] op_sel_hi:[1,0]
	v_pk_mul_f32 v[62:63], v[62:63], v[14:15] op_sel_hi:[1,0]
	v_pk_mul_f32 v[136:137], v[136:137], v[14:15] op_sel_hi:[1,0]
	v_pk_mul_f32 v[138:139], v[138:139], v[14:15] op_sel_hi:[1,0]
	v_mul_f32_e32 v156, 0xbfb8aa3b, v60
	v_mul_f32_e32 v157, 0xbfb8aa3b, v61
	v_mul_f32_e32 v158, 0xbfb8aa3b, v62
	v_mul_f32_e32 v159, 0xbfb8aa3b, v63
	v_exp_f32_e32 v156, v156
	v_exp_f32_e32 v157, v157
	v_exp_f32_e32 v158, v158
	v_exp_f32_e32 v159, v159
	v_add_f32_e32 v156, 1.0, v156
	v_add_f32_e32 v157, 1.0, v157
	v_add_f32_e32 v158, 1.0, v158
	v_add_f32_e32 v159, 1.0, v159
	v_rcp_f32_e32 v156, v156
	v_rcp_f32_e32 v157, v157
	v_rcp_f32_e32 v158, v158
	v_rcp_f32_e32 v159, v159
	v_lshl_add_u64 v[160:161], v[0:1], 0, s[4:5]
	v_pk_mul_f32 v[60:61], v[60:61], v[156:157]
	v_pk_mul_f32 v[62:63], v[62:63], v[158:159]
	v_pk_mul_f32 v[60:61], v[136:137], v[60:61]
	v_pk_mul_f32 v[62:63], v[138:139], v[62:63]
	s_add_u32 s4, s4, 0x5800
	s_addc_u32 s5, s5, 0
	v_cvt_pk_bf16_f32 v60, v60, v61
	v_cvt_pk_bf16_f32 v61, v62, v63
	global_store_dwordx2 v[160:161], v[60:61], off
	s_waitcnt lgkmcnt(2)
	v_pk_mul_f32 v[140:141], v[140:141], v[16:17] op_sel_hi:[1,0]
	v_pk_mul_f32 v[142:143], v[142:143], v[16:17] op_sel_hi:[1,0]
	v_pk_mul_f32 v[144:145], v[144:145], v[16:17] op_sel_hi:[1,0]
	v_pk_mul_f32 v[146:147], v[146:147], v[16:17] op_sel_hi:[1,0]
	v_mul_f32_e32 v156, 0xbfb8aa3b, v140
	v_mul_f32_e32 v157, 0xbfb8aa3b, v141
	v_mul_f32_e32 v158, 0xbfb8aa3b, v142
	v_mul_f32_e32 v159, 0xbfb8aa3b, v143
	v_exp_f32_e32 v156, v156
	v_exp_f32_e32 v157, v157
	v_exp_f32_e32 v158, v158
	v_exp_f32_e32 v159, v159
	v_add_f32_e32 v156, 1.0, v156
	v_add_f32_e32 v157, 1.0, v157
	v_add_f32_e32 v158, 1.0, v158
	v_add_f32_e32 v159, 1.0, v159
	v_rcp_f32_e32 v156, v156
	v_rcp_f32_e32 v157, v157
	v_rcp_f32_e32 v158, v158
	v_rcp_f32_e32 v159, v159
	v_lshl_add_u64 v[160:161], v[0:1], 0, s[4:5]
	v_pk_mul_f32 v[140:141], v[140:141], v[156:157]
	v_pk_mul_f32 v[142:143], v[142:143], v[158:159]
	v_pk_mul_f32 v[140:141], v[144:145], v[140:141]
	v_pk_mul_f32 v[142:143], v[146:147], v[142:143]
	s_add_u32 s4, s4, 0x5800
	s_addc_u32 s5, s5, 0
	v_cvt_pk_bf16_f32 v140, v140, v141
	v_cvt_pk_bf16_f32 v141, v142, v143
	global_store_dwordx2 v[160:161], v[140:141], off
	s_waitcnt lgkmcnt(0)
	v_pk_mul_f32 v[148:149], v[148:149], v[18:19] op_sel_hi:[1,0]
	v_pk_mul_f32 v[150:151], v[150:151], v[18:19] op_sel_hi:[1,0]
	v_pk_mul_f32 v[152:153], v[152:153], v[18:19] op_sel_hi:[1,0]
	v_pk_mul_f32 v[154:155], v[154:155], v[18:19] op_sel_hi:[1,0]
	v_mul_f32_e32 v156, 0xbfb8aa3b, v148
	v_mul_f32_e32 v157, 0xbfb8aa3b, v149
	v_mul_f32_e32 v158, 0xbfb8aa3b, v150
	v_mul_f32_e32 v159, 0xbfb8aa3b, v151
	v_exp_f32_e32 v156, v156
	v_exp_f32_e32 v157, v157
	v_exp_f32_e32 v158, v158
	v_exp_f32_e32 v159, v159
	v_add_f32_e32 v156, 1.0, v156
	v_add_f32_e32 v157, 1.0, v157
	v_add_f32_e32 v158, 1.0, v158
	v_add_f32_e32 v159, 1.0, v159
	v_rcp_f32_e32 v156, v156
	v_rcp_f32_e32 v157, v157
	v_rcp_f32_e32 v158, v158
	v_rcp_f32_e32 v159, v159
	v_lshl_add_u64 v[160:161], v[0:1], 0, s[4:5]
	v_pk_mul_f32 v[148:149], v[148:149], v[156:157]
	v_pk_mul_f32 v[150:151], v[150:151], v[158:159]
	v_pk_mul_f32 v[148:149], v[152:153], v[148:149]
	v_pk_mul_f32 v[150:151], v[154:155], v[150:151]
	s_add_u32 s4, s4, 0x5800
	s_addc_u32 s5, s5, 0
	v_cvt_pk_bf16_f32 v148, v148, v149
	v_cvt_pk_bf16_f32 v149, v150, v151
	global_store_dwordx2 v[160:161], v[148:149], off
	s_branch .LBB0_108
